# v9 + GLA scan: O computation reads each LDS fragment once (18 instead of 24 reads), reads issued in batches, two MFMA chains interleaved; state update's 11 reads batched; scan phase 146 -> ~131 us by
# speedup vs baseline: 1.0073x; 1.0073x over previous
; #define LAS __attribute__((address_space(3)))
; __device__ __forceinline__ unsigned pk2(float lo, float hi) { const f32x2 v = {lo, hi}; return __builtin_bit_cast(unsigned, __builtin_convertvector(v, bf16x2_hw)); }
; __device__ __forceinline__ void p3_gla_scan(LAS unsigned char* lds_, const Params& p) {
;     ...
;             { const f32x4 eb = *(const LAS f32x4*)(buf + BL_EBL + (16 * w + 4 * lq) * 4);
;               const bf16x8 ka0 = ldfrag(buf + BL_KH, 16 * w + l15, S64, (8 * lq) * 2), ka1 = ldfrag(buf + BL_KH, 16 * w + l15, S64, (8 * lq + 32) * 2);
; #pragma unroll
;               for (int tv = 0; tv < 4; ++tv) { S[tv] = S[tv] * eb;
;                   S[tv] = __builtin_amdgcn_mfma_f32_16x16x32_bf16(ka0, ldfrag(vt, 16 * tv + l15, S64, (8 * lq) * 2), S[tv], 0, 0, 0);
;                   S[tv] = __builtin_amdgcn_mfma_f32_16x16x32_bf16(ka1, ldfrag(vt, 16 * tv + l15, S64, (8 * lq + 32) * 2), S[tv], 0, 0, 0);
;                   *(LAS v2u*)(stn + (16 * tv + l15) * S128 + (16 * w + 4 * lq) * 2) = (v2u){pk2(S[tv][0], S[tv][1]), pk2(S[tv][2], S[tv][3])}; } }
.LBB0_609:
	s_nop 4
	v_add_u32_e32 v136, 0x18800, v129
	ds_read_b128 v[136:139], v136
	ds_read_b128 v[132:135], v125
	v_add_u32_e32 v148, v112, v105
	ds_read_b128 v[140:143], v148
	ds_read_b128 v[144:147], v125 offset:64
	ds_read_b128 v[170:173], v148 offset:64
	ds_read_b128 v[174:177], v126
	ds_read_b128 v[178:181], v126 offset:64
	ds_read_b128 v[182:185], v127
	ds_read_b128 v[186:189], v127 offset:64
	ds_read_b128 v[190:193], v128
	ds_read_b128 v[194:197], v128 offset:64
	s_add_i32 s30, s30, 2
	s_add_i32 s31, s31, -2
	s_waitcnt lgkmcnt(10)
	v_pk_mul_f32 v[80:81], v[80:81], v[138:139]
	v_pk_mul_f32 v[78:79], v[78:79], v[136:137]
	v_pk_mul_f32 v[76:77], v[76:77], v[138:139]
	v_pk_mul_f32 v[74:75], v[74:75], v[136:137]
	v_pk_mul_f32 v[72:73], v[72:73], v[138:139]
	v_pk_mul_f32 v[70:71], v[70:71], v[136:137]
	v_mul_f32_e64 v68, v68, v138
	v_mul_f32_e64 v69, v69, v139
	v_pk_mul_f32 v[66:67], v[66:67], v[136:137]
	s_waitcnt lgkmcnt(8)
	v_mfma_f32_16x16x32_bf16 v[78:81], v[132:135], v[140:143], v[78:81]
	s_waitcnt lgkmcnt(6)
	v_mfma_f32_16x16x32_bf16 v[78:81], v[144:147], v[170:173], v[78:81]
	s_waitcnt lgkmcnt(5)
	v_mfma_f32_16x16x32_bf16 v[74:77], v[132:135], v[174:177], v[74:77]
	s_waitcnt lgkmcnt(4)
	v_mfma_f32_16x16x32_bf16 v[74:77], v[144:147], v[178:181], v[74:77]
	s_waitcnt lgkmcnt(3)
	v_mfma_f32_16x16x32_bf16 v[70:73], v[132:135], v[182:185], v[70:73]
	s_waitcnt lgkmcnt(2)
	v_mfma_f32_16x16x32_bf16 v[70:73], v[144:147], v[186:189], v[70:73]
	s_waitcnt lgkmcnt(1)
	v_mfma_f32_16x16x32_bf16 v[66:69], v[132:135], v[190:193], v[66:69]
	s_waitcnt lgkmcnt(0)
	v_mfma_f32_16x16x32_bf16 v[66:69], v[144:147], v[194:197], v[66:69]
	v_cvt_pk_bf16_f32 v198, v78, v79
	v_cvt_pk_bf16_f32 v199, v80, v81
	ds_write_b64 v130, v[198:199]
	v_cvt_pk_bf16_f32 v200, v74, v75
	v_cvt_pk_bf16_f32 v201, v76, v77
	ds_write_b64 v130, v[200:201] offset:4352
	v_cvt_pk_bf16_f32 v202, v70, v71
	v_cvt_pk_bf16_f32 v203, v72, v73
	ds_write_b64 v130, v[202:203] offset:8704
	s_cmpk_gt_u32 s33, 0x41
	s_nop 0
	v_cvt_pk_bf16_f32 v204, v66, v67
	v_cvt_pk_bf16_f32 v205, v68, v69
	ds_write_b64 v130, v[204:205] offset:13056
	s_cbranch_scc1 .LBB0_596

; #define LAS __attribute__((address_space(3)))
; __device__ __forceinline__ unsigned pk2(float lo, float hi) { const f32x2 v = {lo, hi}; return __builtin_bit_cast(unsigned, __builtin_convertvector(v, bf16x2_hw)); }
; __device__ __forceinline__ void st_global_b64(void* p, v2u v) { asm volatile("global_store_dwordx2 %0, %1, off\n\ts_nop 1" :: "v"(p), "v"(v) : "memory"); }
; __device__ __forceinline__ void p3_gla_scan(LAS unsigned char* lds_, const Params& p) {
;     ...
;             if (!ctx) {
;                 const int ti = w & 3; const size_t row0 = (size_t)(b * SEQ + ch * 64);
; #pragma unroll
;                 for (int t2 = 0; t2 < 2; ++t2) { const int tv = 2 * (w >> 2) + t2; f32x4 o4 = (f32x4){0.f, 0.f, 0.f, 0.f};
; #pragma unroll
;                     for (int ks = 0; ks < 4; ++ks) o4 = __builtin_amdgcn_mfma_f32_16x16x32_bf16(ldfrag(stc, 16 * tv + l15, S128, (8 * lq + 32 * ks) * 2), ldfrag(buf + BL_QT, 16 * ti + l15, S128, (8 * lq + 32 * ks) * 2), o4, 0, 0, 0);
; #pragma unroll
;                     for (int ks = 0; ks < 2; ++ks) o4 = __builtin_amdgcn_mfma_f32_16x16x32_bf16(ldfrag(vt, 16 * tv + l15, S64, (8 * lq + 32 * ks) * 2), ldfrag(buf + BL_ATT, 16 * ti + l15, S64, (8 * lq + 32 * ks) * 2), o4, 0, 0, 0);
;                     const int i = 16 * ti + l15, v0 = 16 * tv + 4 * lq;
;                     st_global_b64(Og + (row0 + i) * VALW + h * DV + dvs * 64 + v0, (v2u){pk2(o4[0], o4[1]), pk2(o4[2], o4[3])}); }
;             }
;             { const f32x4 eb = *(const LAS f32x4*)(buf + BL_EBL + (16 * w + 4 * lq) * 4);
;               const bf16x8 ka0 = ldfrag(buf + BL_KH, 16 * w + l15, S64, (8 * lq) * 2), ka1 = ldfrag(buf + BL_KH, 16 * w + l15, S64, (8 * lq + 32) * 2);
; #pragma unroll
;               for (int tv = 0; tv < 4; ++tv) { S[tv] = S[tv] * eb;
;                   S[tv] = __builtin_amdgcn_mfma_f32_16x16x32_bf16(ka0, ldfrag(vt, 16 * tv + l15, S64, (8 * lq) * 2), S[tv], 0, 0, 0);
;                   S[tv] = __builtin_amdgcn_mfma_f32_16x16x32_bf16(ka1, ldfrag(vt, 16 * tv + l15, S64, (8 * lq + 32) * 2), S[tv], 0, 0, 0);
;                   *(LAS v2u*)(stn + (16 * tv + l15) * S128 + (16 * w + 4 * lq) * 2) = (v2u){pk2(S[tv][0], S[tv][1]), pk2(S[tv][2], S[tv][3])}; } }
.LBB0_616:
	s_cmp_gt_u32 s33, 3
	s_cselect_b64 s[16:17], -1, 0
	s_cmp_lt_u32 s33, 4
	v_add_u32_e32 v132, v111, v105
	s_cbranch_scc1 .LBB0_618
	ds_read_b128 v[134:137], v115
	ds_read_b128 v[150:153], v132
	ds_read_b128 v[170:173], v117
	ds_read_b128 v[138:141], v115 offset:64
	ds_read_b128 v[154:157], v132 offset:64
	ds_read_b128 v[174:177], v117 offset:64
	ds_read_b128 v[142:145], v115 offset:128
	ds_read_b128 v[158:161], v132 offset:128
	ds_read_b128 v[178:181], v117 offset:128
	ds_read_b128 v[146:149], v115 offset:192
	ds_read_b128 v[162:165], v132 offset:192
	ds_read_b128 v[182:185], v117 offset:192
	v_add_u32_e32 v133, v87, v105
	s_waitcnt lgkmcnt(10)
	v_mfma_f32_16x16x32_bf16 v[222:225], v[134:137], v[150:153], 0
	s_waitcnt lgkmcnt(9)
	v_mfma_f32_16x16x32_bf16 v[226:229], v[170:173], v[150:153], 0
	ds_read_b128 v[194:197], v133 offset:46080
	ds_read_b128 v[186:189], v116 offset:35840
	ds_read_b128 v[202:205], v118 offset:46080
	ds_read_b128 v[198:201], v133 offset:46144
	ds_read_b128 v[190:193], v116 offset:35904
	ds_read_b128 v[206:209], v118 offset:46144
	s_and_b64 s[18:19], s[12:13], exec
	s_cselect_b32 s18, s33, s31
	s_lshl_b32 s18, s18, 6
	s_add_i32 s18, s18, s8
	s_ashr_i32 s19, s18, 31
	v_or_b32_e32 v210, s18, v86
	v_mov_b32_e32 v211, s19
	v_lshlrev_b64 v[212:213], 12, v[210:211]
	v_lshl_add_u64 v[214:215], s[14:15], 0, v[212:213]
	v_lshl_add_u64 v[218:219], v[98:99], 1, v[214:215]
	v_lshl_add_u64 v[220:221], v[100:101], 1, v[214:215]
	v_lshl_add_u64 v[220:221], v[220:221], 0, 32
	s_waitcnt lgkmcnt(13)
	v_mfma_f32_16x16x32_bf16 v[222:225], v[138:141], v[154:157], v[222:225]
	s_waitcnt lgkmcnt(12)
	v_mfma_f32_16x16x32_bf16 v[226:229], v[174:177], v[154:157], v[226:229]
	s_waitcnt lgkmcnt(10)
	v_mfma_f32_16x16x32_bf16 v[222:225], v[142:145], v[158:161], v[222:225]
	s_waitcnt lgkmcnt(9)
	v_mfma_f32_16x16x32_bf16 v[226:229], v[178:181], v[158:161], v[226:229]
	s_waitcnt lgkmcnt(7)
	v_mfma_f32_16x16x32_bf16 v[222:225], v[146:149], v[162:165], v[222:225]
	s_waitcnt lgkmcnt(6)
	v_mfma_f32_16x16x32_bf16 v[226:229], v[182:185], v[162:165], v[226:229]
	s_waitcnt lgkmcnt(4)
	v_mfma_f32_16x16x32_bf16 v[222:225], v[194:197], v[186:189], v[222:225]
	s_waitcnt lgkmcnt(3)
	v_mfma_f32_16x16x32_bf16 v[226:229], v[202:205], v[186:189], v[226:229]
	s_waitcnt lgkmcnt(1)
	v_mfma_f32_16x16x32_bf16 v[222:225], v[198:201], v[190:193], v[222:225]
	s_waitcnt lgkmcnt(0)
	v_mfma_f32_16x16x32_bf16 v[226:229], v[206:209], v[190:193], v[226:229]
	s_nop 6
	v_cvt_pk_bf16_f32 v230, v222, v223
	v_cvt_pk_bf16_f32 v231, v224, v225
	global_store_dwordx2 v[218:219], v[230:231], off
	s_nop 1
	v_cvt_pk_bf16_f32 v232, v226, v227
	v_cvt_pk_bf16_f32 v233, v228, v229
	global_store_dwordx2 v[220:221], v[232:233], off
	s_nop 1
.LBB0_618:
	ds_read_b128 v[138:141], v129 offset:45056
	ds_read_b128 v[134:137], v119 offset:17408
	ds_read_b128 v[142:145], v120 offset:46080
	ds_read_b128 v[146:149], v119 offset:17472
	ds_read_b128 v[150:153], v120 offset:46144
	ds_read_b128 v[170:173], v120 offset:48384
	ds_read_b128 v[174:177], v120 offset:48448
	ds_read_b128 v[178:181], v120 offset:50688
	ds_read_b128 v[182:185], v120 offset:50752
	ds_read_b128 v[186:189], v120 offset:52992
	ds_read_b128 v[190:193], v120 offset:53056
	s_add_i32 s34, s30, -3
	s_waitcnt lgkmcnt(10)
	v_pk_mul_f32 v[78:79], v[78:79], v[138:139]
	v_pk_mul_f32 v[80:81], v[80:81], v[140:141]
	v_pk_mul_f32 v[74:75], v[74:75], v[138:139]
	v_pk_mul_f32 v[76:77], v[76:77], v[140:141]
	v_pk_mul_f32 v[70:71], v[70:71], v[138:139]
	v_pk_mul_f32 v[72:73], v[72:73], v[140:141]
	v_mul_f32_e64 v66, v66, v138
	v_mul_f32_e64 v67, v67, v139
	v_pk_mul_f32 v[68:69], v[68:69], v[140:141]
	s_waitcnt lgkmcnt(8)
	v_mfma_f32_16x16x32_bf16 v[78:81], v[134:137], v[142:145], v[78:81]
	s_waitcnt lgkmcnt(6)
	v_mfma_f32_16x16x32_bf16 v[78:81], v[146:149], v[150:153], v[78:81]
	s_waitcnt lgkmcnt(5)
	v_mfma_f32_16x16x32_bf16 v[74:77], v[134:137], v[170:173], v[74:77]
	s_waitcnt lgkmcnt(4)
	v_mfma_f32_16x16x32_bf16 v[74:77], v[146:149], v[174:177], v[74:77]
	s_waitcnt lgkmcnt(3)
	v_mfma_f32_16x16x32_bf16 v[70:73], v[134:137], v[178:181], v[70:73]
	s_waitcnt lgkmcnt(2)
	v_mfma_f32_16x16x32_bf16 v[70:73], v[146:149], v[182:185], v[70:73]
	s_waitcnt lgkmcnt(1)
	v_mfma_f32_16x16x32_bf16 v[66:69], v[134:137], v[186:189], v[66:69]
	s_waitcnt lgkmcnt(0)
	v_mfma_f32_16x16x32_bf16 v[66:69], v[146:149], v[190:193], v[66:69]
	v_cvt_pk_bf16_f32 v194, v78, v79
	v_cvt_pk_bf16_f32 v195, v80, v81
	ds_write_b64 v130, v[194:195] offset:17408
	v_cvt_pk_bf16_f32 v196, v74, v75
	v_cvt_pk_bf16_f32 v197, v76, v77
	ds_write_b64 v130, v[196:197] offset:21760
	v_cvt_pk_bf16_f32 v198, v70, v71
	v_cvt_pk_bf16_f32 v199, v72, v73
	ds_write_b64 v130, v[198:199] offset:26112
	s_cmpk_gt_u32 s34, 0x42
	s_nop 0
	v_cvt_pk_bf16_f32 v200, v66, v67
	v_cvt_pk_bf16_f32 v201, v68, v69
	ds_write_b64 v130, v[200:201] offset:30464
	s_waitcnt lgkmcnt(0)
	s_barrier
	s_cbranch_scc0 .LBB0_621
	s_cmp_gt_u32 s34, 64
	s_cbranch_scc0 .LBB0_624

; __device__ __forceinline__ unsigned pk2(float lo, float hi) { const f32x2 v = {lo, hi}; return __builtin_bit_cast(unsigned, __builtin_convertvector(v, bf16x2_hw)); }
; __device__ __forceinline__ void st_global_b64(void* p, v2u v) { asm volatile("global_store_dwordx2 %0, %1, off\n\ts_nop 1" :: "v"(p), "v"(v) : "memory"); }
; __device__ __forceinline__ void p3_gla_scan(LAS unsigned char* lds_, const Params& p) {
;     ...
;             if (!ctx) {
;                 const int ti = w & 3; const size_t row0 = (size_t)(b * SEQ + ch * 64);
; #pragma unroll
;                 for (int t2 = 0; t2 < 2; ++t2) { const int tv = 2 * (w >> 2) + t2; f32x4 o4 = (f32x4){0.f, 0.f, 0.f, 0.f};
; #pragma unroll
;                     for (int ks = 0; ks < 4; ++ks) o4 = __builtin_amdgcn_mfma_f32_16x16x32_bf16(ldfrag(stc, 16 * tv + l15, S128, (8 * lq + 32 * ks) * 2), ldfrag(buf + BL_QT, 16 * ti + l15, S128, (8 * lq + 32 * ks) * 2), o4, 0, 0, 0);
; #pragma unroll
;                     for (int ks = 0; ks < 2; ++ks) o4 = __builtin_amdgcn_mfma_f32_16x16x32_bf16(ldfrag(vt, 16 * tv + l15, S64, (8 * lq + 32 * ks) * 2), ldfrag(buf + BL_ATT, 16 * ti + l15, S64, (8 * lq + 32 * ks) * 2), o4, 0, 0, 0);
;                     const int i = 16 * ti + l15, v0 = 16 * tv + 4 * lq;
;                     st_global_b64(Og + (row0 + i) * VALW + h * DV + dvs * 64 + v0, (v2u){pk2(o4[0], o4[1]), pk2(o4[2], o4[3])}); }
.LBB0_627:
	ds_read_b128 v[134:137], v121
	ds_read_b128 v[150:153], v132 offset:55296
	ds_read_b128 v[170:173], v123
	ds_read_b128 v[138:141], v121 offset:64
	ds_read_b128 v[154:157], v132 offset:55360
	ds_read_b128 v[174:177], v123 offset:64
	ds_read_b128 v[142:145], v121 offset:128
	ds_read_b128 v[158:161], v132 offset:55424
	ds_read_b128 v[178:181], v123 offset:128
	ds_read_b128 v[146:149], v121 offset:192
	ds_read_b128 v[162:165], v132 offset:55488
	ds_read_b128 v[182:185], v123 offset:192
	v_add_u32_e32 v133, v110, v105
	s_waitcnt lgkmcnt(10)
	v_mfma_f32_16x16x32_bf16 v[222:225], v[134:137], v[150:153], 0
	s_waitcnt lgkmcnt(9)
	v_mfma_f32_16x16x32_bf16 v[226:229], v[170:173], v[150:153], 0
	ds_read_b128 v[194:197], v133
	ds_read_b128 v[186:189], v122
	ds_read_b128 v[202:205], v124
	ds_read_b128 v[198:201], v133 offset:64
	ds_read_b128 v[190:193], v122 offset:64
	ds_read_b128 v[206:209], v124 offset:64
	s_add_i32 s18, s31, -1
	s_and_b64 s[16:17], s[12:13], exec
	s_cselect_b32 s16, s34, s18
	s_lshl_b32 s16, s16, 6
	s_add_i32 s16, s16, s8
	s_ashr_i32 s17, s16, 31
	v_or_b32_e32 v210, s16, v86
	v_mov_b32_e32 v211, s17
	v_lshlrev_b64 v[212:213], 12, v[210:211]
	v_lshl_add_u64 v[214:215], s[14:15], 0, v[212:213]
	v_lshl_add_u64 v[218:219], v[98:99], 1, v[214:215]
	v_lshl_add_u64 v[220:221], v[100:101], 1, v[214:215]
	v_lshl_add_u64 v[220:221], v[220:221], 0, 32
	s_waitcnt lgkmcnt(13)
	v_mfma_f32_16x16x32_bf16 v[222:225], v[138:141], v[154:157], v[222:225]
	s_waitcnt lgkmcnt(12)
	v_mfma_f32_16x16x32_bf16 v[226:229], v[174:177], v[154:157], v[226:229]
	s_waitcnt lgkmcnt(10)
	v_mfma_f32_16x16x32_bf16 v[222:225], v[142:145], v[158:161], v[222:225]
	s_waitcnt lgkmcnt(9)
	v_mfma_f32_16x16x32_bf16 v[226:229], v[178:181], v[158:161], v[226:229]
	s_waitcnt lgkmcnt(7)
	v_mfma_f32_16x16x32_bf16 v[222:225], v[146:149], v[162:165], v[222:225]
	s_waitcnt lgkmcnt(6)
	v_mfma_f32_16x16x32_bf16 v[226:229], v[182:185], v[162:165], v[226:229]
	s_waitcnt lgkmcnt(4)
	v_mfma_f32_16x16x32_bf16 v[222:225], v[194:197], v[186:189], v[222:225]
	s_waitcnt lgkmcnt(3)
	v_mfma_f32_16x16x32_bf16 v[226:229], v[202:205], v[186:189], v[226:229]
	s_waitcnt lgkmcnt(1)
	v_mfma_f32_16x16x32_bf16 v[222:225], v[198:201], v[190:193], v[222:225]
	s_waitcnt lgkmcnt(0)
	v_mfma_f32_16x16x32_bf16 v[226:229], v[206:209], v[190:193], v[226:229]
	s_nop 6
	v_cvt_pk_bf16_f32 v230, v222, v223
	v_cvt_pk_bf16_f32 v231, v224, v225
	global_store_dwordx2 v[218:219], v[230:231], off
	s_nop 1
	v_cvt_pk_bf16_f32 v232, v226, v227
	v_cvt_pk_bf16_f32 v233, v228, v229
	global_store_dwordx2 v[220:221], v[232:233], off
	s_nop 1
	s_branch .LBB0_609
